# P5 epilogue: output-gate loads of column groups 1-2 hoisted above the first stores
# speedup vs baseline: 1.0091x; 1.0091x over previous
; #define LAS __attribute__((address_space(3)))
; __device__ __forceinline__ unsigned pk2(float lo, float hi) { f32x2_t v = {lo, hi}; bf16x2_t b = __builtin_convertvector(v, bf16x2_t); return __builtin_bit_cast(unsigned, b); }
; #define MFMA32(a, b, c) __builtin_amdgcn_mfma_f32_32x32x16_bf16((a), (b), (c), 0, 0, 0)
;     __device__ __forceinline__ bf16* U() const { return (bf16*)(ws + WS_U); }
;     __device__ __forceinline__ bf16* KVt() const { return (bf16*)(ws + WS_KVT); }
; template <bool SAMPLE>
; __device__ __forceinline__ void mout_task(Ctx& C, int l, int unit, int h, int tb, const LAS float* cwl, const LAS float* gainl, LAS float* gsbuf, LAS s16x8* qfl, const bool st) {
;     ...
;     for (int sb = 0; sb < nsb; ++sb) {
;         f32x16 S;
; #pragma unroll
;         for (int i = 0; i < 16; ++i) S[i] = 0.f;
;         const int sl = 32 * sb + r;
;         { s16x8 tk[8];
;           const bf16* kp = C.U() + (grow0 + sl) * UW + C_KM + h * 128 + 8 * hi;
; #pragma unroll
;           for (int ks = 0; ks < 8; ++ks) tk[ks] = *(const s16x8*)(kp + 16 * ks);
; #pragma unroll
;           for (int ks = 0; ks < 8; ++ks) S = MFMA32(tk[ks], qfl[ks * 64 + lane], S); }
;         const float e0 = (bt - mt) * LOG2E;
; #pragma unroll
;         for (int i4 = 0; i4 < 4; ++i4) { const f32x4 gs = *(const LAS f32x4*)(gsbuf + 32 * sb + 8 * i4 + 4 * hi);
; #pragma unroll
;             for (int e = 0; e < 4; ++e) { const int sidx = 32 * sb + 8 * i4 + 4 * hi + e;
;                 const float wv = (sidx <= tl) ? __builtin_amdgcn_exp2f(e0 + gs[e] * LOG2E) : 0.f;
;                 S[4 * i4 + e] *= wv; den += S[4 * i4 + e]; } }
; #pragma unroll
;         for (int s2 = 0; s2 < 2; ++s2) { u32x4 w; w.x = pk2(S[8 * s2], S[8 * s2 + 1]); w.y = pk2(S[8 * s2 + 2], S[8 * s2 + 3]); w.z = pk2(S[8 * s2 + 4], S[8 * s2 + 5]); w.w = pk2(S[8 * s2 + 6], S[8 * s2 + 7]);
;             const s16x8 pf = __builtin_bit_cast(s16x8, w);
;             const bf16* vp0 = C.KVt() + (size_t)(R_VM + h * 128 + r) * MT + grow0 + 32 * sb + 16 * s2 + 4 * hi;
; #pragma unroll
;             for (int vb = 0; vb < 4; ++vb) { const bf16* vp = vp0 + (size_t)(32 * vb) * MT;
;                 const u32x2 a = *(const u32x2*)vp, bq = *(const u32x2*)(vp + 8); u32x4 vw; vw.x = a.x; vw.y = a.y; vw.z = bq.x; vw.w = bq.y;
;                 acc[vb] = MFMA32(__builtin_bit_cast(s16x8, vw), pf, acc[vb]); } }
.LBB0_909:
	v_lshl_add_u64 v[68:69], s[90:91], 0, v[138:139]
	global_load_dwordx4 v[64:67], v[68:69], off offset:3072
	global_load_dwordx4 v[140:143], v[68:69], off offset:3104
	global_load_dwordx4 v[160:163], v[68:69], off offset:3136
	global_load_dwordx4 v[164:167], v[68:69], off offset:3168
	global_load_dwordx4 v[168:171], v[68:69], off offset:3200
	global_load_dwordx4 v[172:175], v[68:69], off offset:3232
	global_load_dwordx4 v[176:179], v[68:69], off offset:3264
	global_load_dwordx4 v[180:183], v[68:69], off offset:3296
	v_cmp_gt_u32_e32 vcc, v120, v158
	s_mov_b32 s37, 0x12900000
	s_add_i32 s40, s40, -1
	s_mov_b64 s[72:73], 0x48000
	v_lshl_add_u64 v[138:139], v[138:139], 0, s[72:73]
	s_cmp_lg_u32 s40, 0
	s_waitcnt vmcnt(7) lgkmcnt(7)
	v_mfma_f32_32x32x16_bf16 v[64:79], v[64:67], v[80:83], 0
	s_waitcnt vmcnt(6) lgkmcnt(6)
	v_mfma_f32_32x32x16_bf16 v[64:79], v[140:143], v[84:87], v[64:79]
	s_waitcnt vmcnt(5) lgkmcnt(5)
	v_mfma_f32_32x32x16_bf16 v[64:79], v[160:163], v[88:91], v[64:79]
	ds_read_b128 v[140:143], v157
	ds_read_b128 v[160:163], v157 offset:32
	s_waitcnt lgkmcnt(1)
	v_fmamk_f32 v141, v141, 0x3fb8aa3b, v154
	v_fmamk_f32 v140, v140, 0x3fb8aa3b, v154
	v_exp_f32_e32 v141, v141
	s_waitcnt vmcnt(4)
	v_mfma_f32_32x32x16_bf16 v[64:79], v[164:167], v[92:95], v[64:79]
	v_exp_f32_e32 v140, v140
	v_cndmask_b32_e32 v141, 0, v141, vcc
	v_cmp_le_u32_e32 vcc, v158, v120
	s_nop 1
	v_cndmask_b32_e32 v140, 0, v140, vcc
	s_waitcnt vmcnt(3)
	v_mfma_f32_32x32x16_bf16 v[64:79], v[168:171], v[96:99], v[64:79]
	s_waitcnt vmcnt(2)
	v_mfma_f32_32x32x16_bf16 v[64:79], v[172:175], v[100:103], v[64:79]
	s_waitcnt vmcnt(1)
	v_mfma_f32_32x32x16_bf16 v[64:79], v[176:179], v[104:107], v[64:79]
	s_waitcnt vmcnt(0)
	v_mfma_f32_32x32x16_bf16 v[64:79], v[180:183], v[108:111], v[64:79]
	v_lshl_add_u64 v[190:191], s[90:91], 0, v[136:137]
	s_mov_b64 s[72:73], 0x12900000
	v_lshl_add_u64 v[198:199], v[190:191], 0, s[72:73]
	s_mov_b64 s[72:73], 0x12b10000
	v_lshl_add_u64 v[218:219], v[190:191], 0, s[72:73]
	s_mov_b64 s[72:73], 0x12d20000
	v_lshl_add_u64 v[246:247], v[190:191], 0, s[72:73]
	s_mov_b64 s[72:73], 0x12f30000
	v_lshl_add_u64 v[248:249], v[190:191], 0, s[72:73]
	global_load_dwordx2 v[166:167], v[198:199], off
	global_load_dwordx2 v[168:169], v[198:199], off offset:16
	global_load_dwordx2 v[170:171], v[218:219], off
	global_load_dwordx2 v[172:173], v[218:219], off offset:16
	global_load_dwordx2 v[174:175], v[246:247], off
	global_load_dwordx2 v[176:177], v[246:247], off offset:16
	global_load_dwordx2 v[178:179], v[248:249], off
	global_load_dwordx2 v[180:181], v[248:249], off offset:16
	global_load_dwordx2 v[182:183], v[198:199], off offset:32
	global_load_dwordx2 v[184:185], v[198:199], off offset:48
	global_load_dwordx2 v[186:187], v[218:219], off offset:32
	global_load_dwordx2 v[188:189], v[218:219], off offset:48
	global_load_dwordx2 v[194:195], v[246:247], off offset:32
	global_load_dwordx2 v[196:197], v[246:247], off offset:48
	global_load_dwordx2 v[214:215], v[248:249], off offset:32
	global_load_dwordx2 v[216:217], v[248:249], off offset:48
	v_pk_mul_f32 v[140:141], v[64:65], v[140:141]
	v_fmamk_f32 v65, v143, 0x3fb8aa3b, v154
	v_add_f32_e32 v64, v123, v140
	v_add_f32_e32 v123, v141, v64
	v_fmamk_f32 v64, v142, 0x3fb8aa3b, v154
	v_exp_f32_e32 v65, v65
	v_exp_f32_e32 v64, v64
	v_or_b32_e32 v142, 3, v158
	v_or_b32_e32 v143, 2, v158
	v_cmp_le_u32_e32 vcc, v142, v113
	s_nop 1
	v_cndmask_b32_e32 v65, 0, v65, vcc
	v_cmp_le_u32_e32 vcc, v143, v120
	s_nop 1
	v_cndmask_b32_e32 v64, 0, v64, vcc
	v_pk_mul_f32 v[142:143], v[66:67], v[64:65]
	v_cmp_le_i32_e32 vcc, v158, v155
	v_add_f32_e32 v64, v142, v123
	v_add_f32_e32 v123, v143, v64
	s_waitcnt lgkmcnt(0)
	v_fmamk_f32 v64, v160, 0x3fb8aa3b, v154
	v_exp_f32_e32 v64, v64
	v_fmamk_f32 v65, v162, 0x3fb8aa3b, v154
	v_exp_f32_e32 v65, v65
	v_mov_b32_e32 v66, v69
	v_cndmask_b32_e32 v64, 0, v64, vcc
	v_mul_f32_e32 v159, v68, v64
	v_fmac_f32_e32 v123, v68, v64
	v_fmamk_f32 v64, v161, 0x3fb8aa3b, v154
	v_exp_f32_e32 v64, v64
	v_cmp_le_i32_e32 vcc, v158, v115
	v_mov_b32_e32 v67, v70
	v_mov_b32_e32 v70, v71
	v_cndmask_b32_e32 v65, 0, v65, vcc
	v_cmp_le_i32_e32 vcc, v158, v126
	v_mov_b32_e32 v71, v72
	s_nop 0
	v_cndmask_b32_e32 v64, 0, v64, vcc
	v_pk_mul_f32 v[144:145], v[66:67], v[64:65]
	v_cmp_le_i32_e32 vcc, v158, v117
	v_add_f32_e32 v64, v144, v123
	v_add_f32_e32 v123, v145, v64
	v_fmamk_f32 v64, v163, 0x3fb8aa3b, v154
	v_exp_f32_e32 v68, v64
	ds_read_b128 v[64:67], v157 offset:64
	ds_read_b128 v[160:163], v157 offset:96
	v_add_u32_e32 v157, 0x80, v157
	s_waitcnt lgkmcnt(1)
	v_fmamk_f32 v64, v64, 0x3fb8aa3b, v154
	v_exp_f32_e32 v64, v64
	s_nop 0
	v_cndmask_b32_e32 v69, 0, v64, vcc
	v_cmp_le_i32_e32 vcc, v158, v128
	s_nop 1
	v_cndmask_b32_e32 v68, 0, v68, vcc
	v_pk_mul_f32 v[68:69], v[70:71], v[68:69]
	v_cmp_le_i32_e32 vcc, v158, v119
	v_add_f32_e32 v64, v68, v123
	v_add_f32_e32 v72, v69, v64
	v_fmamk_f32 v64, v65, 0x3fb8aa3b, v154
	v_fmamk_f32 v65, v66, 0x3fb8aa3b, v154
	v_exp_f32_e32 v65, v65
	v_exp_f32_e32 v64, v64
	v_mov_b32_e32 v70, v73
	v_mov_b32_e32 v71, v74
	v_cndmask_b32_e32 v65, 0, v65, vcc
	v_cmp_le_i32_e32 vcc, v158, v130
	v_mov_b32_e32 v66, v75
	s_waitcnt lgkmcnt(0)
; #define LAS __attribute__((address_space(3)))
;     __device__ __forceinline__ bf16* U() const { return (bf16*)(ws + WS_U); }
; template <bool SAMPLE>
; __device__ __forceinline__ void mout_task(Ctx& C, int l, int unit, int h, int tb, const LAS float* cwl, const LAS float* gainl, LAS float* gsbuf, LAS s16x8* qfl, const bool st) {
;     ...
;         const float e0 = (bt - mt) * LOG2E;
; #pragma unroll
;         for (int i4 = 0; i4 < 4; ++i4) { const f32x4 gs = *(const LAS f32x4*)(gsbuf + 32 * sb + 8 * i4 + 4 * hi);
; #pragma unroll
;             for (int e = 0; e < 4; ++e) { const int sidx = 32 * sb + 8 * i4 + 4 * hi + e;
;                 const float wv = (sidx <= tl) ? __builtin_amdgcn_exp2f(e0 + gs[e] * LOG2E) : 0.f;
;                 S[4 * i4 + e] *= wv; den += S[4 * i4 + e]; } }
; #pragma unroll
;         for (int s2 = 0; s2 < 2; ++s2) { u32x4 w; w.x = pk2(S[8 * s2], S[8 * s2 + 1]); w.y = pk2(S[8 * s2 + 2], S[8 * s2 + 3]); w.z = pk2(S[8 * s2 + 4], S[8 * s2 + 5]); w.w = pk2(S[8 * s2 + 6], S[8 * s2 + 7]);
;             const s16x8 pf = __builtin_bit_cast(s16x8, w);
;             const bf16* vp0 = C.KVt() + (size_t)(R_VM + h * 128 + r) * MT + grow0 + 32 * sb + 16 * s2 + 4 * hi;
; #pragma unroll
;             for (int vb = 0; vb < 4; ++vb) { const bf16* vp = vp0 + (size_t)(32 * vb) * MT;
;                 const u32x2 a = *(const u32x2*)vp, bq = *(const u32x2*)(vp + 8); u32x4 vw; vw.x = a.x; vw.y = a.y; vw.z = bq.x; vw.w = bq.y;
;                 acc[vb] = MFMA32(__builtin_bit_cast(s16x8, vw), pf, acc[vb]); } }
;     }
;     den += __shfl_xor(den, 32);
;     den += winter * qn;
;     const float inv = __builtin_amdgcn_rcpf(fmaxf(fabsf(den), fexp(-mt)));
;     float ss = 0.f;
; #pragma unroll
;     for (int vb = 0; vb < 4; ++vb)
; #pragma unroll
;         for (int i = 0; i < 16; ++i) { acc[vb][i] *= inv; ss += acc[vb][i] * acc[vb][i]; }
;     ss += __shfl_xor(ss, 32);
;     const float rn = rsqrtf(ss * (1.f / 128.f) + EPS);
;     int lane2 = lane; asm volatile("" : "+v"(lane2));
;     const int hi2 = lane2 >> 5;
;     bf16* orow = C.U() + (grow0 + 32 * tb + (lane2 & 31)) * UW + C_OM + h * 128;
; #pragma unroll
;     for (int vb = 0; vb < 4; ++vb)
; #pragma unroll
;         for (int i4 = 0; i4 < 4; ++i4) { const int v0 = 32 * vb + 8 * i4 + 4 * hi2;
;             const u32x2 ow = *(const u32x2*)(orow + v0); const f32x4 gn = *(const LAS f32x4*)(gainl + h * 128 + v0);
	v_fmamk_f32 v73, v163, 0x3fb8aa3b, v154
	v_cndmask_b32_e32 v64, 0, v64, vcc
	v_pk_mul_f32 v[70:71], v[70:71], v[64:65]
	v_fmamk_f32 v65, v160, 0x3fb8aa3b, v154
	v_add_f32_e32 v64, v70, v72
	v_add_f32_e32 v72, v71, v64
	v_fmamk_f32 v64, v67, 0x3fb8aa3b, v154
	v_exp_f32_e32 v65, v65
	v_exp_f32_e32 v64, v64
	v_cmp_le_i32_e32 vcc, v158, v121
	v_mov_b32_e32 v67, v76
	v_exp_f32_e32 v73, v73
	v_cndmask_b32_e32 v65, 0, v65, vcc
	v_cmp_le_i32_e32 vcc, v158, v132
	v_mov_b32_e32 v74, v77
	v_mov_b32_e32 v75, v78
	v_cndmask_b32_e32 v64, 0, v64, vcc
	v_pk_mul_f32 v[64:65], v[66:67], v[64:65]
	v_fmamk_f32 v67, v162, 0x3fb8aa3b, v154
	v_fmamk_f32 v66, v161, 0x3fb8aa3b, v154
	v_exp_f32_e32 v67, v67
	v_exp_f32_e32 v66, v66
	v_cmp_le_i32_e32 vcc, v158, v125
	v_lshl_add_u64 v[160:161], s[90:91], 0, v[136:137]
	v_cvt_pk_bf16_f32 v76, v159, v144
	v_cndmask_b32_e32 v67, 0, v67, vcc
	v_cmp_le_i32_e32 vcc, v158, v134
	v_add_f32_e32 v72, v64, v72
	v_lshl_add_u64 v[136:137], v[136:137], 0, 64
	v_cndmask_b32_e32 v66, 0, v66, vcc
	v_cmp_le_i32_e32 vcc, v158, v156
	v_pk_mul_f32 v[66:67], v[74:75], v[66:67]
	v_cvt_pk_bf16_f32 v74, v140, v141
	v_cndmask_b32_e32 v73, 0, v73, vcc
	v_pk_mov_b32 v[140:141], v[144:145], v[68:69] op_sel:[1,0]
	v_add_co_u32_e32 v144, vcc, s37, v160
	v_cvt_pk_bf16_f32 v75, v142, v143
	s_nop 0
	v_addc_co_u32_e32 v145, vcc, 0, v161, vcc
	v_cvt_pk_bf16_f32 v77, v140, v141
	s_mov_b32 s37, 0x12b10000
	v_add_co_u32_e32 v162, vcc, s37, v160
	s_mov_b32 s37, 0x12d20000
	s_nop 0
	v_addc_co_u32_e32 v163, vcc, 0, v161, vcc
	v_add_co_u32_e32 v164, vcc, s37, v160
	s_mov_b32 s37, 0x12f30000
	s_nop 0
	v_addc_co_u32_e32 v165, vcc, 0, v161, vcc
	v_add_co_u32_e32 v160, vcc, s37, v160
	v_pk_mov_b32 v[68:69], v[68:69], v[70:71] op_sel:[1,0]
	s_nop 0
	v_addc_co_u32_e32 v161, vcc, 0, v161, vcc
	v_pk_mov_b32 v[70:71], v[70:71], v[64:65] op_sel:[1,0]
	v_mul_f32_e32 v78, v79, v73
	v_cvt_pk_bf16_f32 v68, v68, v69
	v_cvt_pk_bf16_f32 v69, v70, v71
	v_pk_mov_b32 v[70:71], v[64:65], v[66:67] op_sel:[1,0]
	v_add_f32_e32 v64, v65, v72
	v_cvt_pk_bf16_f32 v70, v70, v71
	s_waitcnt vmcnt(14)
	v_mfma_f32_32x32x16_bf16 v[0:15], v[166:169], v[74:77], v[0:15]
	v_cvt_pk_bf16_f32 v71, v67, v78
	v_add_f32_e32 v64, v66, v64
	v_add_f32_e32 v123, v67, v64
	v_fmac_f32_e32 v123, v79, v73
	v_add_u32_e32 v158, 32, v158
	s_waitcnt vmcnt(12)
	v_mfma_f32_32x32x16_bf16 v[16:31], v[170:173], v[74:77], v[16:31]
	s_waitcnt vmcnt(10)
	v_mfma_f32_32x32x16_bf16 v[32:47], v[174:177], v[74:77], v[32:47]
	s_waitcnt vmcnt(8)
	v_mfma_f32_32x32x16_bf16 v[48:63], v[178:181], v[74:77], v[48:63]
	s_waitcnt vmcnt(6)
	v_mfma_f32_32x32x16_bf16 v[0:15], v[182:185], v[68:71], v[0:15]
	s_waitcnt vmcnt(4)
	v_mfma_f32_32x32x16_bf16 v[16:31], v[186:189], v[68:71], v[16:31]
	s_waitcnt vmcnt(2)
	v_mfma_f32_32x32x16_bf16 v[32:47], v[194:197], v[68:71], v[32:47]
	s_waitcnt vmcnt(0)
	v_mfma_f32_32x32x16_bf16 v[48:63], v[214:217], v[68:71], v[48:63]
	s_cbranch_scc1 .LBB0_909
	v_mov_b32_e32 v66, v112
	s_mov_b64 s[18:19], 0x1000
	v_and_or_b32 v64, v66, 31, s39
	v_or_b32_e32 v67, s20, v64
	v_mov_b64_e32 v[64:65], s[90:91]
	v_mad_u64_u32 v[64:65], s[72:73], v67, s61, v[64:65]
	v_ashrrev_i32_e32 v66, 3, v66
	v_mad_i32_i24 v65, s21, v221, v65
	v_and_b32_e32 v66, -4, v66
	v_lshl_add_u64 v[64:65], s[22:23], 1, v[64:65]
	v_ashrrev_i32_e32 v67, 31, v66
	v_lshl_add_u64 v[64:65], v[66:67], 1, v[64:65]
	v_add_co_u32_e32 v76, vcc, s60, v64
	v_lshl_add_u64 v[72:73], v[64:65], 0, s[18:19]
	s_nop 0
	v_addc_co_u32_e32 v77, vcc, 0, v65, vcc
	global_load_dwordx2 v[78:79], v[76:77], off
	global_load_dwordx2 v[80:81], v[72:73], off offset:16
	global_load_dwordx2 v[86:87], v[72:73], off offset:32
	global_load_dwordx2 v[82:83], v[72:73], off offset:48
	global_load_dwordx2 v[196:197], v[72:73], off offset:64
	global_load_dwordx2 v[198:199], v[72:73], off offset:80
	global_load_dwordx2 v[214:215], v[72:73], off offset:96
	global_load_dwordx2 v[216:217], v[72:73], off offset:112
	global_load_dwordx2 v[218:219], v[72:73], off offset:128
	global_load_dwordx2 v[224:225], v[72:73], off offset:144
	global_load_dwordx2 v[242:243], v[72:73], off offset:160
	global_load_dwordx2 v[246:247], v[72:73], off offset:176
	v_xor_b32_e32 v64, 32, v220
	v_add_u32_e32 v65, 64, v133
	v_cmp_lt_i32_e32 vcc, v64, v65
	v_mul_f32_e32 v67, 0xbfb8aa3b, v153
	v_exp_f32_e32 v67, v67
	v_cndmask_b32_e32 v64, v220, v64, vcc
	v_lshlrev_b32_e32 v125, 2, v64
	ds_bpermute_b32 v64, v125, v122
	ds_bpermute_b32 v65, v125, v123
	s_lshl_b32 s20, s22, 2
	s_add_i32 s20, s20, 0
	v_lshl_add_u32 v103, v66, 2, s20
	s_cmp_eq_u32 s47, 0
	s_waitcnt lgkmcnt(0)
; #define LAS __attribute__((address_space(3)))
; __device__ __forceinline__ float bflo(unsigned w) { return __uint_as_float(w << 16); }
; __device__ __forceinline__ float bfhi(unsigned w) { return __uint_as_float(w & 0xffff0000u); }
; __device__ __forceinline__ float fexp(float x) { return __builtin_amdgcn_exp2f(x * LOG2E); }
; __device__ __forceinline__ float sigmoidf_(float x) { return __builtin_amdgcn_rcpf(1.f + fexp(-x)); }
;     __device__ __forceinline__ bf16* U() const { return (bf16*)(ws + WS_U); }
; template <bool SAMPLE>
; __device__ __forceinline__ void mout_task(Ctx& C, int l, int unit, int h, int tb, const LAS float* cwl, const LAS float* gainl, LAS float* gsbuf, LAS s16x8* qfl, const bool st) {
;     ...
;     den += __shfl_xor(den, 32);
;     den += winter * qn;
;     const float inv = __builtin_amdgcn_rcpf(fmaxf(fabsf(den), fexp(-mt)));
;     float ss = 0.f;
; #pragma unroll
;     for (int vb = 0; vb < 4; ++vb)
; #pragma unroll
;         for (int i = 0; i < 16; ++i) { acc[vb][i] *= inv; ss += acc[vb][i] * acc[vb][i]; }
;     ss += __shfl_xor(ss, 32);
;     const float rn = rsqrtf(ss * (1.f / 128.f) + EPS);
;     int lane2 = lane; asm volatile("" : "+v"(lane2));
;     const int hi2 = lane2 >> 5;
;     bf16* orow = C.U() + (grow0 + 32 * tb + (lane2 & 31)) * UW + C_OM + h * 128;
; #pragma unroll
;     for (int vb = 0; vb < 4; ++vb)
; #pragma unroll
;         for (int i4 = 0; i4 < 4; ++i4) { const int v0 = 32 * vb + 8 * i4 + 4 * hi2;
;             const u32x2 ow = *(const u32x2*)(orow + v0); const f32x4 gn = *(const LAS f32x4*)(gainl + h * 128 + v0);
;             const float y0 = acc[vb][4 * i4] * rn * gn[0] * sigmoidf_(bflo(ow.x)), y1 = acc[vb][4 * i4 + 1] * rn * gn[1] * sigmoidf_(bfhi(ow.x));
;             const float y2 = acc[vb][4 * i4 + 2] * rn * gn[2] * sigmoidf_(bflo(ow.y)), y3 = acc[vb][4 * i4 + 3] * rn * gn[3] * sigmoidf_(bfhi(ow.y));
	v_pk_add_f32 v[64:65], v[122:123], v[64:65]
	s_cselect_b64 s[20:21], -1, 0
	v_fmac_f32_e32 v65, v124, v64
	v_max_f32_e64 v64, |v65|, v67
	v_rcp_f32_e32 v102, v64
	ds_read_b128 v[68:71], v103 offset:20480
	ds_read_b128 v[64:67], v103 offset:20512
	ds_read_b128 v[136:139], v103 offset:20544
	ds_read_b128 v[140:143], v103 offset:20576
	s_cmp_lt_u32 s78, 64
	v_pk_mul_f32 v[94:95], v[0:1], v[102:103] op_sel_hi:[1,0]
	v_pk_mul_f32 v[92:93], v[2:3], v[102:103] op_sel_hi:[1,0]
	v_pk_mul_f32 v[74:75], v[58:59], v[102:103] op_sel_hi:[1,0]
	v_pk_mul_f32 v[58:59], v[62:63], v[102:103] op_sel_hi:[1,0]
	v_pk_mul_f32 v[88:89], v[4:5], v[102:103] op_sel_hi:[1,0]
	v_pk_mul_f32 v[144:145], v[94:95], v[94:95]
	v_pk_mul_f32 v[60:61], v[60:61], v[102:103] op_sel_hi:[1,0]
	v_pk_mul_f32 v[84:85], v[6:7], v[102:103] op_sel_hi:[1,0]
	v_pk_mul_f32 v[122:123], v[92:93], v[92:93]
	v_pk_mul_f32 v[160:161], v[10:11], v[102:103] op_sel_hi:[1,0]
	v_pk_mul_f32 v[164:165], v[8:9], v[102:103] op_sel_hi:[1,0]
	v_pk_mul_f32 v[170:171], v[14:15], v[102:103] op_sel_hi:[1,0]
	v_pk_mul_f32 v[174:175], v[12:13], v[102:103] op_sel_hi:[1,0]
	v_pk_mul_f32 v[90:91], v[18:19], v[102:103] op_sel_hi:[1,0]
	v_pk_mul_f32 v[96:97], v[16:17], v[102:103] op_sel_hi:[1,0]
	v_pk_mul_f32 v[30:31], v[30:31], v[102:103] op_sel_hi:[1,0]
	v_pk_mul_f32 v[28:29], v[28:29], v[102:103] op_sel_hi:[1,0]
	v_pk_mul_f32 v[16:17], v[42:43], v[102:103] op_sel_hi:[1,0]
	v_pk_mul_f32 v[18:19], v[40:41], v[102:103] op_sel_hi:[1,0]
	v_pk_mul_f32 v[12:13], v[46:47], v[102:103] op_sel_hi:[1,0]
	v_pk_mul_f32 v[14:15], v[44:45], v[102:103] op_sel_hi:[1,0]
	v_pk_mul_f32 v[8:9], v[50:51], v[102:103] op_sel_hi:[1,0]
	v_pk_mul_f32 v[10:11], v[48:49], v[102:103] op_sel_hi:[1,0]
	v_pk_mul_f32 v[154:155], v[88:89], v[88:89]
	v_pk_mul_f32 v[120:121], v[84:85], v[84:85]
	v_pk_mul_f32 v[166:167], v[164:165], v[164:165]
	v_pk_mul_f32 v[162:163], v[160:161], v[160:161]
	v_pk_mul_f32 v[176:177], v[174:175], v[174:175]
	v_pk_mul_f32 v[172:173], v[170:171], v[170:171]
	v_pk_mul_f32 v[180:181], v[96:97], v[96:97]
	v_pk_mul_f32 v[178:179], v[90:91], v[90:91]
	v_pk_mul_f32 v[194:195], v[28:29], v[28:29]
	v_pk_mul_f32 v[190:191], v[30:31], v[30:31]
	v_pk_mul_f32 v[40:41], v[18:19], v[18:19]
	v_pk_mul_f32 v[42:43], v[16:17], v[16:17]
	v_pk_mul_f32 v[44:45], v[14:15], v[14:15]
	v_pk_mul_f32 v[46:47], v[12:13], v[12:13]
	v_pk_mul_f32 v[48:49], v[10:11], v[10:11]
	v_pk_mul_f32 v[50:51], v[8:9], v[8:9]
	v_pk_mul_f32 v[100:101], v[74:75], v[74:75]
	v_pk_mul_f32 v[98:99], v[60:61], v[60:61]
	v_pk_mul_f32 v[6:7], v[58:59], v[58:59]
	s_cselect_b64 s[22:23], -1, 0
	s_and_b64 s[20:21], s[20:21], s[22:23]
	s_cmpk_lt_i32 s2, 0x80
	s_cselect_b64 s[22:23], -1, 0
	s_and_b64 s[20:21], s[20:21], s[22:23]
	v_readlane_b32 s74, v255, 43
	v_readlane_b32 s39, v255, 42
	v_readlane_b32 s75, v255, 44
	s_movk_i32 s80, 0x1ff
	s_movk_i32 s37, 0xffc2
	s_waitcnt vmcnt(11)
	v_and_b32_e32 v1, 0xffff0000, v78
	v_lshlrev_b32_e32 v0, 16, v78
	s_waitcnt vmcnt(9)
	v_lshlrev_b32_e32 v78, 16, v86
	v_mul_f32_e32 v1, 0xbfb8aa3b, v1
	v_lshlrev_b32_e32 v2, 16, v79
	v_mul_f32_e32 v0, 0xbfb8aa3b, v0
	v_mul_f32_e32 v78, 0xbfb8aa3b, v78
	v_exp_f32_e32 v1, v1
	v_mul_f32_e32 v2, 0xbfb8aa3b, v2
	v_exp_f32_e32 v0, v0
	v_exp_f32_e32 v78, v78
	v_exp_f32_e32 v2, v2
	v_add_f32_e32 v1, 1.0, v1
	v_and_b32_e32 v3, 0xffff0000, v79
	v_and_b32_e32 v79, 0xffff0000, v86
	v_add_f32_e32 v0, 1.0, v0
	v_rcp_f32_e32 v111, v1
	v_add_f32_e32 v1, 1.0, v78
	v_add_f32_e32 v2, 1.0, v2
	v_rcp_f32_e32 v110, v0
	v_mul_f32_e32 v0, 0xbfb8aa3b, v79
	v_rcp_f32_e32 v156, v1
	v_lshlrev_b32_e32 v1, 16, v87
	v_rcp_f32_e32 v108, v2
	v_exp_f32_e32 v0, v0
	v_mul_f32_e32 v1, 0xbfb8aa3b, v1
	v_and_b32_e32 v2, 0xffff0000, v87
	v_exp_f32_e32 v1, v1
	v_mul_f32_e32 v2, 0xbfb8aa3b, v2
	v_exp_f32_e32 v2, v2
	v_add_f32_e32 v0, 1.0, v0
	v_rcp_f32_e32 v157, v0
	v_add_f32_e32 v0, 1.0, v1
	v_rcp_f32_e32 v158, v0
	v_add_f32_e32 v0, 1.0, v2
	v_rcp_f32_e32 v159, v0
	s_waitcnt vmcnt(8)
	v_lshlrev_b32_e32 v0, 16, v82
	v_mul_f32_e32 v0, 0xbfb8aa3b, v0
	v_and_b32_e32 v1, 0xffff0000, v82
	v_exp_f32_e32 v0, v0
	v_mul_f32_e32 v1, 0xbfb8aa3b, v1
	v_lshlrev_b32_e32 v4, 16, v80
	v_and_b32_e32 v5, 0xffff0000, v80
	v_lshlrev_b32_e32 v62, 16, v81
	v_and_b32_e32 v63, 0xffff0000, v81
	v_exp_f32_e32 v1, v1
	v_mul_f32_e32 v3, 0xbfb8aa3b, v3
	v_mul_f32_e32 v4, 0xbfb8aa3b, v4
	v_mul_f32_e32 v5, 0xbfb8aa3b, v5
	v_mul_f32_e32 v62, 0xbfb8aa3b, v62
	v_mul_f32_e32 v63, 0xbfb8aa3b, v63
	v_exp_f32_e32 v3, v3
	v_exp_f32_e32 v4, v4
	v_exp_f32_e32 v5, v5
	v_exp_f32_e32 v62, v62
	v_exp_f32_e32 v63, v63
	v_add_f32_e32 v0, 1.0, v0
	v_rcp_f32_e32 v168, v0
	v_add_f32_e32 v0, 1.0, v1
	v_rcp_f32_e32 v169, v0
	v_lshlrev_b32_e32 v0, 16, v83
	v_add_f32_e32 v3, 1.0, v3
	v_add_f32_e32 v4, 1.0, v4
	v_add_f32_e32 v5, 1.0, v5
	v_add_f32_e32 v62, 1.0, v62
	v_add_f32_e32 v63, 1.0, v63
	v_mul_f32_e32 v0, 0xbfb8aa3b, v0
	v_rcp_f32_e32 v109, v3
	v_rcp_f32_e32 v106, v4
	v_rcp_f32_e32 v107, v5
	v_rcp_f32_e32 v104, v62
	v_rcp_f32_e32 v105, v63
	v_exp_f32_e32 v82, v0
	v_pk_mul_f32 v[80:81], v[22:23], v[102:103] op_sel_hi:[1,0]
	v_pk_mul_f32 v[86:87], v[20:21], v[102:103] op_sel_hi:[1,0]
	v_pk_mul_f32 v[62:63], v[26:27], v[102:103] op_sel_hi:[1,0]
	v_pk_mul_f32 v[78:79], v[24:25], v[102:103] op_sel_hi:[1,0]
	v_pk_mul_f32 v[24:25], v[34:35], v[102:103] op_sel_hi:[1,0]
	v_pk_mul_f32 v[26:27], v[32:33], v[102:103] op_sel_hi:[1,0]
	v_pk_mul_f32 v[20:21], v[38:39], v[102:103] op_sel_hi:[1,0]
	v_pk_mul_f32 v[22:23], v[36:37], v[102:103] op_sel_hi:[1,0]
	v_pk_mul_f32 v[2:3], v[54:55], v[102:103] op_sel_hi:[1,0]
	v_pk_mul_f32 v[4:5], v[52:53], v[102:103] op_sel_hi:[1,0]
; #define LAS __attribute__((address_space(3)))
; __device__ __forceinline__ unsigned pk2(float lo, float hi) { f32x2_t v = {lo, hi}; bf16x2_t b = __builtin_convertvector(v, bf16x2_t); return __builtin_bit_cast(unsigned, b); }
; __device__ __forceinline__ float bflo(unsigned w) { return __uint_as_float(w << 16); }
; __device__ __forceinline__ float bfhi(unsigned w) { return __uint_as_float(w & 0xffff0000u); }
; __device__ __forceinline__ float sigmoidf_(float x) { return __builtin_amdgcn_rcpf(1.f + fexp(-x)); }
;     __device__ __forceinline__ bf16* U() const { return (bf16*)(ws + WS_U); }
; template <bool SAMPLE>
; __device__ __forceinline__ void mout_task(Ctx& C, int l, int unit, int h, int tb, const LAS float* cwl, const LAS float* gainl, LAS float* gsbuf, LAS s16x8* qfl, const bool st) {
;     ...
;     float ss = 0.f;
; #pragma unroll
;     for (int vb = 0; vb < 4; ++vb)
; #pragma unroll
;         for (int i = 0; i < 16; ++i) { acc[vb][i] *= inv; ss += acc[vb][i] * acc[vb][i]; }
;     ss += __shfl_xor(ss, 32);
;     const float rn = rsqrtf(ss * (1.f / 128.f) + EPS);
;     int lane2 = lane; asm volatile("" : "+v"(lane2));
;     const int hi2 = lane2 >> 5;
;     bf16* orow = C.U() + (grow0 + 32 * tb + (lane2 & 31)) * UW + C_OM + h * 128;
; #pragma unroll
;     for (int vb = 0; vb < 4; ++vb)
; #pragma unroll
;         for (int i4 = 0; i4 < 4; ++i4) { const int v0 = 32 * vb + 8 * i4 + 4 * hi2;
;             const u32x2 ow = *(const u32x2*)(orow + v0); const f32x4 gn = *(const LAS f32x4*)(gainl + h * 128 + v0);
;             const float y0 = acc[vb][4 * i4] * rn * gn[0] * sigmoidf_(bflo(ow.x)), y1 = acc[vb][4 * i4 + 1] * rn * gn[1] * sigmoidf_(bfhi(ow.x));
;             const float y2 = acc[vb][4 * i4 + 2] * rn * gn[2] * sigmoidf_(bflo(ow.y)), y3 = acc[vb][4 * i4 + 3] * rn * gn[3] * sigmoidf_(bfhi(ow.y));
;             u32x2 w; w.x = pk2(y0, y1); w.y = pk2(y2, y3); if (st) *(u32x2*)(orow + v0) = w; if (i4 == 3) asm volatile("" ::: "memory"); }
	v_pk_mul_f32 v[0:1], v[56:57], v[102:103] op_sel_hi:[1,0]
	v_add_f32_e32 v102, v144, v145
	v_add_f32_e32 v102, v122, v102
	v_add_f32_e32 v102, v123, v102
	v_add_f32_e32 v102, v154, v102
	v_add_f32_e32 v102, v155, v102
	v_add_f32_e32 v102, v120, v102
	v_add_f32_e32 v102, v121, v102
	v_add_f32_e32 v102, v166, v102
	v_add_f32_e32 v102, v167, v102
	v_add_f32_e32 v102, v162, v102
	v_add_f32_e32 v102, v163, v102
	v_add_f32_e32 v102, v176, v102
	v_add_f32_e32 v102, v177, v102
	v_add_f32_e32 v102, v172, v102
	v_add_f32_e32 v102, v173, v102
	v_add_f32_e32 v102, v180, v102
	v_add_f32_e32 v102, v181, v102
	v_add_f32_e32 v102, v178, v102
	v_pk_mul_f32 v[184:185], v[86:87], v[86:87]
	v_add_f32_e32 v102, v179, v102
	v_add_f32_e32 v102, v184, v102
	v_pk_mul_f32 v[182:183], v[80:81], v[80:81]
	v_add_f32_e32 v102, v185, v102
	v_add_f32_e32 v102, v182, v102
	v_pk_mul_f32 v[188:189], v[78:79], v[78:79]
	v_add_f32_e32 v102, v183, v102
	v_add_f32_e32 v102, v188, v102
	v_pk_mul_f32 v[186:187], v[62:63], v[62:63]
	v_add_f32_e32 v102, v189, v102
	v_add_f32_e32 v102, v186, v102
	v_add_f32_e32 v102, v187, v102
	v_add_f32_e32 v102, v194, v102
	v_add_f32_e32 v102, v195, v102
	v_add_f32_e32 v102, v190, v102
	v_pk_mul_f32 v[32:33], v[26:27], v[26:27]
	v_add_f32_e32 v102, v191, v102
	v_add_f32_e32 v32, v32, v102
	v_pk_mul_f32 v[34:35], v[24:25], v[24:25]
	v_add_f32_e32 v32, v33, v32
	v_add_f32_e32 v32, v34, v32
	v_pk_mul_f32 v[36:37], v[22:23], v[22:23]
	v_add_f32_e32 v32, v35, v32
	v_add_f32_e32 v32, v36, v32
	v_pk_mul_f32 v[38:39], v[20:21], v[20:21]
	v_add_f32_e32 v32, v37, v32
	v_add_f32_e32 v32, v38, v32
	v_add_f32_e32 v32, v39, v32
	v_add_f32_e32 v32, v40, v32
	v_add_f32_e32 v32, v41, v32
	v_add_f32_e32 v32, v42, v32
	v_add_f32_e32 v32, v43, v32
	v_add_f32_e32 v32, v44, v32
	v_add_f32_e32 v32, v45, v32
	v_add_f32_e32 v32, v46, v32
	v_add_f32_e32 v32, v47, v32
	v_add_f32_e32 v32, v48, v32
	v_add_f32_e32 v32, v49, v32
	v_add_f32_e32 v32, v50, v32
	v_pk_mul_f32 v[52:53], v[4:5], v[4:5]
	v_add_f32_e32 v32, v51, v32
	v_add_f32_e32 v32, v52, v32
	v_pk_mul_f32 v[54:55], v[2:3], v[2:3]
	v_add_f32_e32 v32, v53, v32
	v_add_f32_e32 v32, v54, v32
	v_pk_mul_f32 v[56:57], v[0:1], v[0:1]
	v_add_f32_e32 v32, v55, v32
	v_add_f32_e32 v32, v56, v32
	v_add_f32_e32 v32, v57, v32
	v_add_f32_e32 v32, v100, v32
	v_add_f32_e32 v32, v101, v32
	v_add_f32_e32 v32, v98, v32
	v_add_f32_e32 v32, v99, v32
	v_add_f32_e32 v6, v6, v32
	v_add_f32_e32 v6, v7, v6
	ds_bpermute_b32 v7, v125, v6
	v_mov_b32_e32 v34, 0x358637bd
	v_and_b32_e32 v33, 0xffff0000, v83
	v_mul_f32_e32 v33, 0xbfb8aa3b, v33
	v_exp_f32_e32 v33, v33
	s_waitcnt lgkmcnt(0)
	v_add_f32_e32 v6, v6, v7
	v_fmamk_f32 v6, v6, 0x3c000000, v34
	v_mul_f32_e32 v7, 0x4b800000, v6
	v_cmp_gt_f32_e32 vcc, s65, v6
	v_add_f32_e32 v32, 1.0, v82
	v_rcp_f32_e32 v32, v32
	v_cndmask_b32_e32 v6, v6, v7, vcc
	v_rsq_f32_e32 v6, v6
	v_add_f32_e32 v7, 1.0, v33
	v_rcp_f32_e32 v33, v7
	v_mul_f32_e32 v7, 0x45800000, v6
	v_cndmask_b32_e32 v6, v6, v7, vcc
	v_pk_mul_f32 v[34:35], v[94:95], v[6:7] op_sel_hi:[1,0]
	v_pk_mul_f32 v[36:37], v[92:93], v[6:7] op_sel_hi:[1,0]
	v_pk_mul_f32 v[34:35], v[68:69], v[34:35]
	v_pk_mul_f32 v[36:37], v[70:71], v[36:37]
	v_pk_mul_f32 v[34:35], v[110:111], v[34:35]
	v_pk_mul_f32 v[36:37], v[108:109], v[36:37]
	v_cvt_pk_bf16_f32 v34, v34, v35
	v_cvt_pk_bf16_f32 v35, v36, v37
	global_store_dwordx2 v[76:77], v[34:35], off
	v_pk_mul_f32 v[34:35], v[88:89], v[6:7] op_sel_hi:[1,0]
	v_pk_mul_f32 v[36:37], v[84:85], v[6:7] op_sel_hi:[1,0]
	v_pk_mul_f32 v[34:35], v[64:65], v[34:35]
	v_pk_mul_f32 v[36:37], v[66:67], v[36:37]
	v_pk_mul_f32 v[34:35], v[106:107], v[34:35]
	v_pk_mul_f32 v[36:37], v[104:105], v[36:37]
	v_cvt_pk_bf16_f32 v34, v34, v35
	v_cvt_pk_bf16_f32 v35, v36, v37
	global_store_dwordx2 v[72:73], v[34:35], off offset:16
	v_pk_mul_f32 v[34:35], v[164:165], v[6:7] op_sel_hi:[1,0]
	v_pk_mul_f32 v[36:37], v[160:161], v[6:7] op_sel_hi:[1,0]
	v_pk_mul_f32 v[34:35], v[136:137], v[34:35]
	v_pk_mul_f32 v[36:37], v[138:139], v[36:37]
	v_pk_mul_f32 v[34:35], v[156:157], v[34:35]
	v_pk_mul_f32 v[36:37], v[158:159], v[36:37]
	v_cvt_pk_bf16_f32 v34, v34, v35
	v_cvt_pk_bf16_f32 v35, v36, v37
	global_store_dwordx2 v[72:73], v[34:35], off offset:32
	v_pk_mul_f32 v[34:35], v[174:175], v[6:7] op_sel_hi:[1,0]
	v_pk_mul_f32 v[36:37], v[170:171], v[6:7] op_sel_hi:[1,0]
	v_pk_mul_f32 v[34:35], v[140:141], v[34:35]
	v_pk_mul_f32 v[36:37], v[142:143], v[36:37]
	v_pk_mul_f32 v[34:35], v[168:169], v[34:35]
	v_pk_mul_f32 v[32:33], v[32:33], v[36:37]
	v_cvt_pk_bf16_f32 v34, v34, v35
	v_cvt_pk_bf16_f32 v35, v32, v33
	global_store_dwordx2 v[72:73], v[34:35], off offset:48
	s_waitcnt vmcnt(4)
	v_mov_b64_e32 v[40:41], v[196:197]
	v_mov_b64_e32 v[42:43], v[198:199]
	v_mov_b64_e32 v[44:45], v[214:215]
	v_mov_b64_e32 v[46:47], v[216:217]
	ds_read_b128 v[32:35], v103 offset:20608
	ds_read_b128 v[36:39], v103 offset:20640
	s_andn2_b64 vcc, exec, s[20:21]
	s_nop 0
	v_lshlrev_b32_e32 v7, 16, v40
	v_mul_f32_e32 v7, 0xbfb8aa3b, v7
	v_exp_f32_e32 v7, v7
	v_and_b32_e32 v40, 0xffff0000, v40
	v_mul_f32_e32 v40, 0xbfb8aa3b, v40
	v_exp_f32_e32 v50, v40
	v_add_f32_e32 v7, 1.0, v7
	v_pk_mul_f32 v[48:49], v[96:97], v[6:7] op_sel_hi:[1,0]
	v_rcp_f32_e32 v40, v7
	s_waitcnt lgkmcnt(1)
; #define LAS __attribute__((address_space(3)))
; __device__ __forceinline__ unsigned pk2(float lo, float hi) { f32x2_t v = {lo, hi}; bf16x2_t b = __builtin_convertvector(v, bf16x2_t); return __builtin_bit_cast(unsigned, b); }
; __device__ __forceinline__ float bflo(unsigned w) { return __uint_as_float(w << 16); }
; __device__ __forceinline__ float bfhi(unsigned w) { return __uint_as_float(w & 0xffff0000u); }
; __device__ __forceinline__ float sigmoidf_(float x) { return __builtin_amdgcn_rcpf(1.f + fexp(-x)); }
; template <bool SAMPLE>
; __device__ __forceinline__ void mout_task(Ctx& C, int l, int unit, int h, int tb, const LAS float* cwl, const LAS float* gainl, LAS float* gsbuf, LAS s16x8* qfl, const bool st) {
;     ...
; #pragma unroll
;     for (int vb = 0; vb < 4; ++vb)
; #pragma unroll
;         for (int i4 = 0; i4 < 4; ++i4) { const int v0 = 32 * vb + 8 * i4 + 4 * hi2;
;             const u32x2 ow = *(const u32x2*)(orow + v0); const f32x4 gn = *(const LAS f32x4*)(gainl + h * 128 + v0);
;             const float y0 = acc[vb][4 * i4] * rn * gn[0] * sigmoidf_(bflo(ow.x)), y1 = acc[vb][4 * i4 + 1] * rn * gn[1] * sigmoidf_(bfhi(ow.x));
;             const float y2 = acc[vb][4 * i4 + 2] * rn * gn[2] * sigmoidf_(bflo(ow.y)), y3 = acc[vb][4 * i4 + 3] * rn * gn[3] * sigmoidf_(bfhi(ow.y));
;             u32x2 w; w.x = pk2(y0, y1); w.y = pk2(y2, y3); if (st) *(u32x2*)(orow + v0) = w; if (i4 == 3) asm volatile("" ::: "memory"); }
	v_pk_mul_f32 v[32:33], v[32:33], v[48:49]
	v_lshlrev_b32_e32 v48, 16, v41
	v_mul_f32_e32 v48, 0xbfb8aa3b, v48
	v_and_b32_e32 v41, 0xffff0000, v41
	v_exp_f32_e32 v48, v48
	v_mul_f32_e32 v41, 0xbfb8aa3b, v41
	v_exp_f32_e32 v49, v41
	v_add_f32_e32 v7, 1.0, v50
	v_rcp_f32_e32 v41, v7
	v_add_f32_e32 v7, 1.0, v48
	v_rcp_f32_e32 v48, v7
	v_add_f32_e32 v7, 1.0, v49
	v_rcp_f32_e32 v49, v7
	v_pk_mul_f32 v[32:33], v[40:41], v[32:33]
	v_pk_mul_f32 v[40:41], v[90:91], v[6:7] op_sel_hi:[1,0]
	s_nop 0
	v_lshlrev_b32_e32 v7, 16, v42
	v_pk_mul_f32 v[34:35], v[34:35], v[40:41]
	v_cvt_pk_bf16_f32 v32, v32, v33
	v_pk_mul_f32 v[34:35], v[48:49], v[34:35]
	v_mul_f32_e32 v7, 0xbfb8aa3b, v7
	v_cvt_pk_bf16_f32 v33, v34, v35
	global_store_dwordx2 v[72:73], v[32:33], off offset:64
	v_and_b32_e32 v32, 0xffff0000, v42
	v_exp_f32_e32 v7, v7
	v_mul_f32_e32 v32, 0xbfb8aa3b, v32
	v_exp_f32_e32 v33, v32
	s_nop 0
	v_lshlrev_b32_e32 v41, 16, v45
	v_add_f32_e32 v7, 1.0, v7
	v_rcp_f32_e32 v32, v7
	v_pk_mul_f32 v[34:35], v[86:87], v[6:7] op_sel_hi:[1,0]
	v_add_f32_e32 v7, 1.0, v33
	v_lshlrev_b32_e32 v33, 16, v43
	v_mul_f32_e32 v33, 0xbfb8aa3b, v33
	s_waitcnt lgkmcnt(0)
	v_pk_mul_f32 v[34:35], v[36:37], v[34:35]
	v_exp_f32_e32 v36, v33
	v_and_b32_e32 v33, 0xffff0000, v43
	v_mul_f32_e32 v33, 0xbfb8aa3b, v33
	v_exp_f32_e32 v37, v33
	v_rcp_f32_e32 v33, v7
	v_add_f32_e32 v7, 1.0, v36
	v_rcp_f32_e32 v36, v7
	v_add_f32_e32 v7, 1.0, v37
	v_rcp_f32_e32 v37, v7
	v_pk_mul_f32 v[32:33], v[32:33], v[34:35]
	v_pk_mul_f32 v[34:35], v[80:81], v[6:7] op_sel_hi:[1,0]
	v_lshlrev_b32_e32 v7, 16, v44
	v_mul_f32_e32 v7, 0xbfb8aa3b, v7
	v_exp_f32_e32 v7, v7
	v_pk_mul_f32 v[34:35], v[38:39], v[34:35]
	v_cvt_pk_bf16_f32 v32, v32, v33
	v_pk_mul_f32 v[34:35], v[36:37], v[34:35]
	v_add_f32_e32 v7, 1.0, v7
	v_rcp_f32_e32 v40, v7
	v_and_b32_e32 v7, 0xffff0000, v44
	v_cvt_pk_bf16_f32 v33, v34, v35
	v_mul_f32_e32 v7, 0xbfb8aa3b, v7
	global_store_dwordx2 v[72:73], v[32:33], off offset:80
	ds_read_b128 v[32:35], v103 offset:20672
	ds_read_b128 v[36:39], v103 offset:20704
	v_exp_f32_e32 v7, v7
	v_mul_f32_e32 v41, 0xbfb8aa3b, v41
	v_pk_mul_f32 v[42:43], v[78:79], v[6:7] op_sel_hi:[1,0]
	s_waitcnt lgkmcnt(1)
	v_pk_mul_f32 v[32:33], v[32:33], v[42:43]
	v_exp_f32_e32 v42, v41
	v_and_b32_e32 v41, 0xffff0000, v45
	v_mul_f32_e32 v41, 0xbfb8aa3b, v41
	v_exp_f32_e32 v43, v41
	v_add_f32_e32 v7, 1.0, v7
	v_rcp_f32_e32 v41, v7
	v_add_f32_e32 v7, 1.0, v42
	v_rcp_f32_e32 v42, v7
	v_add_f32_e32 v7, 1.0, v43
	v_rcp_f32_e32 v43, v7
	v_pk_mul_f32 v[32:33], v[40:41], v[32:33]
	v_pk_mul_f32 v[40:41], v[62:63], v[6:7] op_sel_hi:[1,0]
	s_nop 0
	v_lshlrev_b32_e32 v7, 16, v46
	v_pk_mul_f32 v[34:35], v[34:35], v[40:41]
	v_cvt_pk_bf16_f32 v32, v32, v33
	v_pk_mul_f32 v[34:35], v[42:43], v[34:35]
	v_mul_f32_e32 v7, 0xbfb8aa3b, v7
	v_cvt_pk_bf16_f32 v33, v34, v35
	global_store_dwordx2 v[72:73], v[32:33], off offset:96
	v_and_b32_e32 v32, 0xffff0000, v46
	v_exp_f32_e32 v7, v7
	v_mul_f32_e32 v32, 0xbfb8aa3b, v32
	v_exp_f32_e32 v33, v32
	v_add_f32_e32 v7, 1.0, v7
	v_rcp_f32_e32 v32, v7
	v_pk_mul_f32 v[28:29], v[28:29], v[6:7] op_sel_hi:[1,0]
	v_add_f32_e32 v7, 1.0, v33
	v_lshlrev_b32_e32 v33, 16, v47
	v_mul_f32_e32 v33, 0xbfb8aa3b, v33
	v_exp_f32_e32 v34, v33
	v_and_b32_e32 v33, 0xffff0000, v47
	v_mul_f32_e32 v33, 0xbfb8aa3b, v33
	v_exp_f32_e32 v35, v33
	v_rcp_f32_e32 v33, v7
	v_add_f32_e32 v7, 1.0, v34
	v_rcp_f32_e32 v34, v7
	v_add_f32_e32 v7, 1.0, v35
	v_rcp_f32_e32 v35, v7
	v_pk_mul_f32 v[30:31], v[30:31], v[6:7] op_sel_hi:[1,0]
	s_waitcnt lgkmcnt(0)
	v_pk_mul_f32 v[28:29], v[36:37], v[28:29]
	v_pk_mul_f32 v[30:31], v[38:39], v[30:31]
	v_pk_mul_f32 v[28:29], v[32:33], v[28:29]
	v_pk_mul_f32 v[30:31], v[34:35], v[30:31]
	v_cvt_pk_bf16_f32 v28, v28, v29
	v_cvt_pk_bf16_f32 v29, v30, v31
	global_store_dwordx2 v[72:73], v[28:29], off offset:112
	v_mov_b64_e32 v[36:37], v[218:219]
	v_mov_b64_e32 v[38:39], v[224:225]
	v_mov_b64_e32 v[40:41], v[242:243]
	v_mov_b64_e32 v[42:43], v[246:247]
	ds_read_b128 v[28:31], v103 offset:20736
	ds_read_b128 v[32:35], v103 offset:20768
	s_nop 0
	v_lshlrev_b32_e32 v7, 16, v36
	v_mul_f32_e32 v7, 0xbfb8aa3b, v7
	v_exp_f32_e32 v7, v7
	v_and_b32_e32 v36, 0xffff0000, v36
	v_mul_f32_e32 v36, 0xbfb8aa3b, v36
	v_exp_f32_e32 v44, v36
	v_add_f32_e32 v7, 1.0, v7
	v_pk_mul_f32 v[26:27], v[26:27], v[6:7] op_sel_hi:[1,0]
	v_rcp_f32_e32 v36, v7
	s_waitcnt lgkmcnt(1)
	v_pk_mul_f32 v[26:27], v[28:29], v[26:27]
	v_lshlrev_b32_e32 v28, 16, v37
	v_mul_f32_e32 v28, 0xbfb8aa3b, v28
	v_and_b32_e32 v29, 0xffff0000, v37
	v_exp_f32_e32 v28, v28
	v_mul_f32_e32 v29, 0xbfb8aa3b, v29
	v_exp_f32_e32 v29, v29
	v_add_f32_e32 v7, 1.0, v44
	v_rcp_f32_e32 v37, v7
	v_add_f32_e32 v7, 1.0, v28
	v_rcp_f32_e32 v28, v7
	v_add_f32_e32 v7, 1.0, v29
	v_rcp_f32_e32 v29, v7
	v_pk_mul_f32 v[24:25], v[24:25], v[6:7] op_sel_hi:[1,0]
	v_pk_mul_f32 v[26:27], v[36:37], v[26:27]
	v_pk_mul_f32 v[24:25], v[30:31], v[24:25]
	s_nop 0
	v_lshlrev_b32_e32 v7, 16, v38
	v_pk_mul_f32 v[24:25], v[28:29], v[24:25]
	v_mul_f32_e32 v7, 0xbfb8aa3b, v7
	v_cvt_pk_bf16_f32 v26, v26, v27
	v_cvt_pk_bf16_f32 v27, v24, v25
	v_and_b32_e32 v24, 0xffff0000, v38
	v_exp_f32_e32 v7, v7
	v_mul_f32_e32 v24, 0xbfb8aa3b, v24
	v_exp_f32_e32 v25, v24
	global_store_dwordx2 v[72:73], v[26:27], off offset:128
	v_add_f32_e32 v7, 1.0, v7
	v_rcp_f32_e32 v24, v7
	v_pk_mul_f32 v[22:23], v[22:23], v[6:7] op_sel_hi:[1,0]
	v_add_f32_e32 v7, 1.0, v25
	v_lshlrev_b32_e32 v25, 16, v39
	v_mul_f32_e32 v25, 0xbfb8aa3b, v25
	v_exp_f32_e32 v26, v25
	v_and_b32_e32 v25, 0xffff0000, v39
	v_mul_f32_e32 v25, 0xbfb8aa3b, v25
	v_exp_f32_e32 v27, v25
	v_rcp_f32_e32 v25, v7
	v_add_f32_e32 v7, 1.0, v26
	v_rcp_f32_e32 v26, v7
	v_add_f32_e32 v7, 1.0, v27
	v_rcp_f32_e32 v27, v7
	v_pk_mul_f32 v[20:21], v[20:21], v[6:7] op_sel_hi:[1,0]
	s_nop 0
	v_lshlrev_b32_e32 v7, 16, v40
	v_mul_f32_e32 v7, 0xbfb8aa3b, v7
	v_exp_f32_e32 v7, v7
	s_waitcnt lgkmcnt(0)
; #define LAS __attribute__((address_space(3)))
; __device__ __forceinline__ unsigned pk2(float lo, float hi) { f32x2_t v = {lo, hi}; bf16x2_t b = __builtin_convertvector(v, bf16x2_t); return __builtin_bit_cast(unsigned, b); }
; __device__ __forceinline__ float bflo(unsigned w) { return __uint_as_float(w << 16); }
; __device__ __forceinline__ float bfhi(unsigned w) { return __uint_as_float(w & 0xffff0000u); }
; __device__ __forceinline__ float sigmoidf_(float x) { return __builtin_amdgcn_rcpf(1.f + fexp(-x)); }
; template <bool SAMPLE>
; __device__ __forceinline__ void mout_task(Ctx& C, int l, int unit, int h, int tb, const LAS float* cwl, const LAS float* gainl, LAS float* gsbuf, LAS s16x8* qfl, const bool st) {
;     ...
; #pragma unroll
;     for (int vb = 0; vb < 4; ++vb)
; #pragma unroll
;         for (int i4 = 0; i4 < 4; ++i4) { const int v0 = 32 * vb + 8 * i4 + 4 * hi2;
;             const u32x2 ow = *(const u32x2*)(orow + v0); const f32x4 gn = *(const LAS f32x4*)(gainl + h * 128 + v0);
;             const float y0 = acc[vb][4 * i4] * rn * gn[0] * sigmoidf_(bflo(ow.x)), y1 = acc[vb][4 * i4 + 1] * rn * gn[1] * sigmoidf_(bfhi(ow.x));
;             const float y2 = acc[vb][4 * i4 + 2] * rn * gn[2] * sigmoidf_(bflo(ow.y)), y3 = acc[vb][4 * i4 + 3] * rn * gn[3] * sigmoidf_(bfhi(ow.y));
;             u32x2 w; w.x = pk2(y0, y1); w.y = pk2(y2, y3); if (st) *(u32x2*)(orow + v0) = w; if (i4 == 3) asm volatile("" ::: "memory"); }
	v_pk_mul_f32 v[22:23], v[32:33], v[22:23]
	v_pk_mul_f32 v[20:21], v[34:35], v[20:21]
	v_pk_mul_f32 v[22:23], v[24:25], v[22:23]
	v_add_f32_e32 v7, 1.0, v7
	v_pk_mul_f32 v[20:21], v[26:27], v[20:21]
	v_rcp_f32_e32 v28, v7
	v_and_b32_e32 v7, 0xffff0000, v40
	v_cvt_pk_bf16_f32 v22, v22, v23
	v_cvt_pk_bf16_f32 v23, v20, v21
	v_mul_f32_e32 v7, 0xbfb8aa3b, v7
	global_store_dwordx2 v[72:73], v[22:23], off offset:144
	ds_read_b128 v[20:23], v103 offset:20800
	ds_read_b128 v[24:27], v103 offset:20832
	v_exp_f32_e32 v7, v7
	s_nop 0
	v_pk_mul_f32 v[18:19], v[18:19], v[6:7] op_sel_hi:[1,0]
	s_waitcnt lgkmcnt(1)
	v_pk_mul_f32 v[18:19], v[20:21], v[18:19]
	v_lshlrev_b32_e32 v20, 16, v41
	v_mul_f32_e32 v20, 0xbfb8aa3b, v20
	v_and_b32_e32 v21, 0xffff0000, v41
	v_exp_f32_e32 v20, v20
	v_mul_f32_e32 v21, 0xbfb8aa3b, v21
	v_exp_f32_e32 v21, v21
	v_add_f32_e32 v7, 1.0, v7
	v_rcp_f32_e32 v29, v7
	v_add_f32_e32 v7, 1.0, v20
	v_rcp_f32_e32 v20, v7
	v_add_f32_e32 v7, 1.0, v21
	v_rcp_f32_e32 v21, v7
	v_pk_mul_f32 v[16:17], v[16:17], v[6:7] op_sel_hi:[1,0]
	v_pk_mul_f32 v[18:19], v[28:29], v[18:19]
	v_pk_mul_f32 v[16:17], v[22:23], v[16:17]
	s_nop 0
	v_lshlrev_b32_e32 v7, 16, v42
	v_pk_mul_f32 v[16:17], v[20:21], v[16:17]
	v_mul_f32_e32 v7, 0xbfb8aa3b, v7
	v_cvt_pk_bf16_f32 v18, v18, v19
	v_cvt_pk_bf16_f32 v19, v16, v17
	v_and_b32_e32 v16, 0xffff0000, v42
	v_exp_f32_e32 v7, v7
	v_mul_f32_e32 v16, 0xbfb8aa3b, v16
	v_exp_f32_e32 v17, v16
	global_store_dwordx2 v[72:73], v[18:19], off offset:160
	v_add_f32_e32 v7, 1.0, v7
	v_rcp_f32_e32 v16, v7
	v_pk_mul_f32 v[14:15], v[14:15], v[6:7] op_sel_hi:[1,0]
	v_add_f32_e32 v7, 1.0, v17
	v_lshlrev_b32_e32 v17, 16, v43
	v_mul_f32_e32 v17, 0xbfb8aa3b, v17
	v_exp_f32_e32 v18, v17
	v_and_b32_e32 v17, 0xffff0000, v43
	v_mul_f32_e32 v17, 0xbfb8aa3b, v17
	v_exp_f32_e32 v19, v17
	v_rcp_f32_e32 v17, v7
	v_add_f32_e32 v7, 1.0, v18
	v_rcp_f32_e32 v18, v7
	v_add_f32_e32 v7, 1.0, v19
	v_rcp_f32_e32 v19, v7
	v_pk_mul_f32 v[12:13], v[12:13], v[6:7] op_sel_hi:[1,0]
	s_waitcnt lgkmcnt(0)
	v_pk_mul_f32 v[14:15], v[24:25], v[14:15]
	v_pk_mul_f32 v[12:13], v[26:27], v[12:13]
	v_pk_mul_f32 v[14:15], v[16:17], v[14:15]
	v_pk_mul_f32 v[12:13], v[18:19], v[12:13]
	v_cvt_pk_bf16_f32 v14, v14, v15
	v_cvt_pk_bf16_f32 v15, v12, v13
	global_store_dwordx2 v[72:73], v[14:15], off offset:176
	global_load_dwordx2 v[20:21], v[72:73], off offset:192
	global_load_dwordx2 v[22:23], v[72:73], off offset:208
	global_load_dwordx2 v[24:25], v[72:73], off offset:224
	global_load_dwordx2 v[26:27], v[72:73], off offset:240
	ds_read_b128 v[12:15], v103 offset:20864
	ds_read_b128 v[16:19], v103 offset:20896
	s_waitcnt vmcnt(3)
	v_lshlrev_b32_e32 v7, 16, v20
	v_mul_f32_e32 v7, 0xbfb8aa3b, v7
	v_exp_f32_e32 v7, v7
	v_and_b32_e32 v20, 0xffff0000, v20
	v_mul_f32_e32 v20, 0xbfb8aa3b, v20
	v_exp_f32_e32 v28, v20
	v_add_f32_e32 v7, 1.0, v7
	v_pk_mul_f32 v[10:11], v[10:11], v[6:7] op_sel_hi:[1,0]
	v_rcp_f32_e32 v20, v7
	s_waitcnt lgkmcnt(1)
	v_pk_mul_f32 v[10:11], v[12:13], v[10:11]
	v_lshlrev_b32_e32 v12, 16, v21
	v_mul_f32_e32 v12, 0xbfb8aa3b, v12
	v_and_b32_e32 v13, 0xffff0000, v21
	v_exp_f32_e32 v12, v12
	v_mul_f32_e32 v13, 0xbfb8aa3b, v13
	v_exp_f32_e32 v13, v13
	v_add_f32_e32 v7, 1.0, v28
	v_rcp_f32_e32 v21, v7
	v_add_f32_e32 v7, 1.0, v12
	v_rcp_f32_e32 v12, v7
	v_add_f32_e32 v7, 1.0, v13
	v_rcp_f32_e32 v13, v7
	v_pk_mul_f32 v[8:9], v[8:9], v[6:7] op_sel_hi:[1,0]
	v_pk_mul_f32 v[10:11], v[20:21], v[10:11]
	v_pk_mul_f32 v[8:9], v[14:15], v[8:9]
	s_waitcnt vmcnt(2)
	v_lshlrev_b32_e32 v7, 16, v22
	v_pk_mul_f32 v[8:9], v[12:13], v[8:9]
	v_mul_f32_e32 v7, 0xbfb8aa3b, v7
	v_cvt_pk_bf16_f32 v10, v10, v11
	v_cvt_pk_bf16_f32 v11, v8, v9
	v_and_b32_e32 v8, 0xffff0000, v22
	v_exp_f32_e32 v7, v7
	v_mul_f32_e32 v8, 0xbfb8aa3b, v8
	v_exp_f32_e32 v9, v8
	global_store_dwordx2 v[72:73], v[10:11], off offset:192
	v_add_f32_e32 v7, 1.0, v7
	v_rcp_f32_e32 v8, v7
	v_pk_mul_f32 v[4:5], v[4:5], v[6:7] op_sel_hi:[1,0]
	v_add_f32_e32 v7, 1.0, v9
	v_lshlrev_b32_e32 v9, 16, v23
	v_mul_f32_e32 v9, 0xbfb8aa3b, v9
	v_exp_f32_e32 v10, v9
	v_and_b32_e32 v9, 0xffff0000, v23
	v_mul_f32_e32 v9, 0xbfb8aa3b, v9
	v_exp_f32_e32 v11, v9
	v_rcp_f32_e32 v9, v7
	s_waitcnt lgkmcnt(0)
	v_pk_mul_f32 v[4:5], v[16:17], v[4:5]
	v_add_f32_e32 v7, 1.0, v10
	v_rcp_f32_e32 v10, v7
	v_pk_mul_f32 v[4:5], v[8:9], v[4:5]
	v_add_f32_e32 v7, 1.0, v11
	v_cvt_pk_bf16_f32 v4, v4, v5
	s_waitcnt vmcnt(2)
	v_lshlrev_b32_e32 v5, 16, v24
	v_mul_f32_e32 v5, 0xbfb8aa3b, v5
	v_rcp_f32_e32 v11, v7
	v_pk_mul_f32 v[2:3], v[2:3], v[6:7] op_sel_hi:[1,0]
	v_exp_f32_e32 v7, v5
	v_pk_mul_f32 v[2:3], v[18:19], v[2:3]
	v_add_f32_e32 v7, 1.0, v7
	v_pk_mul_f32 v[2:3], v[10:11], v[2:3]
	v_rcp_f32_e32 v12, v7
	v_and_b32_e32 v7, 0xffff0000, v24
	v_cvt_pk_bf16_f32 v5, v2, v3
	v_mul_f32_e32 v7, 0xbfb8aa3b, v7
	global_store_dwordx2 v[72:73], v[4:5], off offset:208
	ds_read_b128 v[2:5], v103 offset:20928
	ds_read_b128 v[8:11], v103 offset:20960
	v_exp_f32_e32 v7, v7
	s_nop 0
	v_pk_mul_f32 v[0:1], v[0:1], v[6:7] op_sel_hi:[1,0]
	s_waitcnt lgkmcnt(1)
	v_pk_mul_f32 v[0:1], v[2:3], v[0:1]
	v_add_f32_e32 v2, 1.0, v7
	v_lshlrev_b32_e32 v3, 16, v25
	v_and_b32_e32 v7, 0xffff0000, v25
	v_mul_f32_e32 v3, 0xbfb8aa3b, v3
	v_mul_f32_e32 v7, 0xbfb8aa3b, v7
	v_exp_f32_e32 v3, v3
	v_exp_f32_e32 v7, v7
	v_rcp_f32_e32 v13, v2
	v_add_f32_e32 v2, 1.0, v3
	v_add_f32_e32 v3, 1.0, v7
	v_rcp_f32_e32 v2, v2
	v_rcp_f32_e32 v3, v3
	v_pk_mul_f32 v[0:1], v[12:13], v[0:1]
	v_pk_mul_f32 v[12:13], v[74:75], v[6:7] op_sel_hi:[1,0]
	v_cvt_pk_bf16_f32 v0, v0, v1
	v_pk_mul_f32 v[4:5], v[4:5], v[12:13]
	s_nop 0
	v_pk_mul_f32 v[2:3], v[2:3], v[4:5]
	s_waitcnt vmcnt(2)
	v_lshlrev_b32_e32 v4, 16, v27
	v_cvt_pk_bf16_f32 v1, v2, v3
	v_lshlrev_b32_e32 v2, 16, v26
	v_and_b32_e32 v3, 0xffff0000, v26
	v_mul_f32_e32 v2, 0xbfb8aa3b, v2
	v_mul_f32_e32 v3, 0xbfb8aa3b, v3
	v_exp_f32_e32 v2, v2
	v_exp_f32_e32 v3, v3
	v_and_b32_e32 v5, 0xffff0000, v27
	v_mul_f32_e32 v4, 0xbfb8aa3b, v4
	v_mul_f32_e32 v5, 0xbfb8aa3b, v5
	v_exp_f32_e32 v4, v4
	v_exp_f32_e32 v5, v5
	global_store_dwordx2 v[72:73], v[0:1], off offset:224
	v_add_f32_e32 v0, 1.0, v2
	v_add_f32_e32 v1, 1.0, v3
	v_rcp_f32_e32 v0, v0
	v_rcp_f32_e32 v1, v1
	v_add_f32_e32 v4, 1.0, v4
	v_add_f32_e32 v5, 1.0, v5
	v_pk_mul_f32 v[2:3], v[60:61], v[6:7] op_sel_hi:[1,0]
	v_rcp_f32_e32 v4, v4
	v_rcp_f32_e32 v5, v5
	s_waitcnt lgkmcnt(0)
	v_pk_mul_f32 v[2:3], v[8:9], v[2:3]
	s_nop 0
	v_pk_mul_f32 v[0:1], v[0:1], v[2:3]
	v_pk_mul_f32 v[2:3], v[58:59], v[6:7] op_sel_hi:[1,0]
	v_cvt_pk_bf16_f32 v0, v0, v1
	v_pk_mul_f32 v[2:3], v[10:11], v[2:3]
	s_nop 0
	v_pk_mul_f32 v[2:3], v[4:5], v[2:3]
	s_nop 0
	v_cvt_pk_bf16_f32 v1, v2, v3
	global_store_dwordx2 v[72:73], v[0:1], off offset:240
	s_waitcnt lgkmcnt(0)
	s_cbranch_vccnz .LBB0_903
;     __device__ __forceinline__ float* GATES() const { return (float*)(ws + WS_GATES); }
;     __device__ __forceinline__ float* MST() const { return (float*)(ws + WS_MB) + 2 * (NSLOT_P + NSLOT_S); }
; template <bool SAMPLE>
; __device__ __forceinline__ void mout_task(Ctx& C, int l, int unit, int h, int tb, const LAS float* cwl, const LAS float* gainl, LAS float* gsbuf, LAS s16x8* qfl, const bool st) {
;     ...
;     const int b = SAMPLE ? unit : unit / NPC, c = SAMPLE ? 0 : unit % NPC;
;     const size_t grow0 = SAMPLE ? (size_t)MP + (size_t)unit * TS : (size_t)b * SEQ + (size_t)c * 64;
;     const int seq0 = SAMPLE ? 0 : c * 64;
;     const int slot = SAMPLE ? NSLOT_P + unit * 4 + h : unit * 4 + h;
;     const float* cleft = C.in[4] + ((size_t)(l * NBD + b) * 3) * 1024;
;     const bool valid = lane < L;
;     const float li = valid ? C.GATES()[(grow0 + lane) * 8 + h] : -1e30f, lf = valid ? C.GATES()[(grow0 + lane) * 8 + 4 + h] : 0.f;
;     const float bc = scan_add(lf, lane);
;     const float gg = valid ? li - bc : -1e30f;
;     const float pmx = scan_max(gg, lane);
;     const float m0 = SAMPLE ? C.in[7][(size_t)l * NSLOT_S + unit * 4 + h] : C.MST()[slot];
; __global__ void __launch_bounds__(512) fwd_megakernel(Args args) {
;     ...
;                 if (it == 0 && C.wave == 0 && C.bid < NBD * 4) mout_task<true>(C, l, C.bid >> 2, C.bid & 3, 0, cwl, gainl, gsb, qfl, st);
	s_ashr_i32 s20, s2, 2
	s_ashr_i32 s21, s20, 31
	s_and_b32 s78, s2, 3
	s_lshl_b64 s[20:21], s[20:21], 5
	s_add_u32 s40, s20, 0x8000
	s_addc_u32 s41, s21, 0
	v_mov_b32_e32 v4, 0xf149f2ca
	v_or_b32_e32 v2, s40, v112
	s_and_saveexec_b64 s[22:23], s[12:13]
	s_cbranch_execz .LBB0_913
	v_mov_b32_e32 v3, s41
	v_readlane_b32 s18, v254, 55
	v_lshlrev_b64 v[0:1], 5, v[2:3]
	v_readlane_b32 s19, v254, 56
	s_lshl_b32 s72, s78, 2
	s_mov_b32 s73, s79
	v_lshl_add_u64 v[0:1], s[18:19], 0, v[0:1]
	v_lshl_add_u64 v[0:1], v[0:1], 0, s[72:73]
	global_load_dword v4, v[0:1], off
